# grid barrier: L1 invalidate issued at arrival (overlapping the wait) instead of after the release
# speedup vs baseline: 1.0141x; 1.0141x over previous
.LBB0_68:
	s_mov_b64 s[8:9], exec
	v_mbcnt_lo_u32_b32 v1, s8, 0
	v_mbcnt_hi_u32_b32 v1, s9, v1
	v_cmp_eq_u32_e32 vcc, 0, v1
	s_and_saveexec_b64 s[6:7], vcc
	s_cbranch_execz .LBB0_70
	s_lshl_b32 s3, s50, 8
	s_add_u32 s10, s12, s3
	s_addc_u32 s11, s13, 0
	s_bcnt1_i32_b64 s3, s[8:9]
	v_mov_b32_e32 v3, 0x1000
	v_mov_b32_e32 v4, s3
	buffer_inv sc1
	global_atomic_add v3, v3, v4, s[10:11] offset:1024 sc0

.LBB0_83:
	s_or_b64 exec, exec, s[8:9]
	s_waitcnt vmcnt(0)
	s_waitcnt vmcnt(0)

.LBB0_101:
	s_or_b64 exec, exec, s[6:7]
	s_waitcnt vmcnt(0)
	s_waitcnt vmcnt(0)

.LBB0_104:
	s_or_b64 exec, exec, s[28:29]
	s_waitcnt vmcnt(0)
	s_waitcnt vmcnt(0)

.LBB0_352:
	s_mov_b64 s[38:39], exec
	v_mbcnt_lo_u32_b32 v0, s38, 0
	v_mbcnt_hi_u32_b32 v0, s39, v0
	v_cmp_eq_u32_e32 vcc, 0, v0
	s_and_saveexec_b64 s[28:29], vcc
	s_cbranch_execz .LBB0_354
	s_bcnt1_i32_b64 s9, s[38:39]
	v_readlane_b32 s38, v241, 9
	v_mov_b32_e32 v4, s9
	v_readlane_b32 s39, v241, 10
	s_nop 4
	buffer_inv sc1
	global_atomic_add v4, v1, v4, s[38:39] sc0

.LBB0_367:
	s_or_b64 exec, exec, s[38:39]
	s_waitcnt vmcnt(0)
	s_waitcnt vmcnt(0)

.LBB0_646:
	s_mov_b64 s[40:41], exec
	v_mbcnt_lo_u32_b32 v0, s40, 0
	v_mbcnt_hi_u32_b32 v0, s41, v0
	v_cmp_eq_u32_e32 vcc, 0, v0
	s_and_saveexec_b64 s[28:29], vcc
	s_cbranch_execz .LBB0_648
	s_bcnt1_i32_b64 s9, s[40:41]
	v_readlane_b32 s40, v241, 9
	v_mov_b32_e32 v4, s9
	v_readlane_b32 s41, v241, 10
	s_nop 4
	buffer_inv sc1
	global_atomic_add v4, v1, v4, s[40:41] sc0

.LBB0_661:
	s_or_b64 exec, exec, s[40:41]
	s_waitcnt vmcnt(0)
	s_waitcnt vmcnt(0)

.LBB0_820:
	s_mov_b64 s[38:39], exec
	v_mbcnt_lo_u32_b32 v0, s38, 0
	v_mbcnt_hi_u32_b32 v0, s39, v0
	v_cmp_eq_u32_e32 vcc, 0, v0
	s_and_saveexec_b64 s[28:29], vcc
	s_cbranch_execz .LBB0_822
	s_bcnt1_i32_b64 s8, s[38:39]
	v_mov_b32_e32 v4, s8
	v_readlane_b32 s8, v241, 9
	v_readlane_b32 s9, v241, 10
	s_nop 4
	buffer_inv sc1
	global_atomic_add v4, v1, v4, s[8:9] sc0
